# init phase: SiLU staging loop of the adaLN item issues its 18 loads together (was load/wait per element), on top of v037
# speedup vs baseline: 1.0029x; 1.0029x over previous
; DI void phase_init(const Ctx& c) {
;     ...
;       for (int i = tid; i < 9 * 1024; i += NTH) {
;         const int b = i >> 10, k = i & 1023;
;         const float v = b < 8 ? P.in[2][b * 1024 + k] : P.in[3][k];
;         sc[i] = v / (1.f + __expf(-v));
;       }
.LBB0_50:
	s_and_saveexec_b64 s[2:3], s[6:7]
	v_readlane_b32 s52, v251, 14
	v_readlane_b32 s58, v251, 20
	v_readlane_b32 s59, v251, 21
	s_mov_b64 s[26:27], 0x800
	v_readlane_b32 s53, v251, 15
	v_readlane_b32 s54, v251, 16
	v_readlane_b32 s55, v251, 17
	v_readlane_b32 s56, v251, 18
	v_readlane_b32 s57, v251, 19
	v_readlane_b32 s60, v251, 22
	v_readlane_b32 s61, v251, 23
	v_readlane_b32 s62, v251, 24
	v_readlane_b32 s63, v251, 25
	v_readlane_b32 s64, v251, 26
	v_readlane_b32 s65, v251, 27
	v_readlane_b32 s66, v251, 28
	v_readlane_b32 s67, v251, 29
	s_cbranch_execz .LBB0_53
	s_mov_b64 s[16:17], 0x1000
	v_mov_b64_e32 v[0:1], v[52:53]
	global_load_dword v80, v[0:1], off
	global_load_dword v81, v[0:1], off offset:2048
	v_lshl_add_u64 v[4:5], v[0:1], 0, s[16:17]
	global_load_dword v82, v[4:5], off
	global_load_dword v83, v[4:5], off offset:2048
	v_lshl_add_u64 v[0:1], v[4:5], 0, s[16:17]
	global_load_dword v84, v[0:1], off
	global_load_dword v85, v[0:1], off offset:2048
	v_lshl_add_u64 v[4:5], v[0:1], 0, s[16:17]
	global_load_dword v86, v[4:5], off
	global_load_dword v87, v[4:5], off offset:2048
	v_lshl_add_u64 v[0:1], v[4:5], 0, s[16:17]
	global_load_dword v88, v[0:1], off
	global_load_dword v89, v[0:1], off offset:2048
	v_lshl_add_u64 v[4:5], v[0:1], 0, s[16:17]
	global_load_dword v90, v[4:5], off
	global_load_dword v91, v[4:5], off offset:2048
	v_lshl_add_u64 v[0:1], v[4:5], 0, s[16:17]
	global_load_dword v92, v[0:1], off
	global_load_dword v93, v[0:1], off offset:2048
	v_lshl_add_u64 v[4:5], v[0:1], 0, s[16:17]
	global_load_dword v94, v[4:5], off
	global_load_dword v95, v[4:5], off offset:2048
	v_lshlrev_b32_e32 v164, 2, v36
	v_lshl_add_u64 v[6:7], s[58:59], 0, v[164:165]
	global_load_dword v96, v[6:7], off
	global_load_dword v97, v[6:7], off offset:2048
	s_waitcnt vmcnt(17)
	v_mul_f32_e32 v5, 0xbfb8aa3b, v80
	v_exp_f32_e32 v5, v5
	s_nop 0
	v_add_f32_e32 v5, 1.0, v5
	v_div_scale_f32 v6, s[24:25], v5, v5, v80
	v_rcp_f32_e32 v7, v6
	v_div_scale_f32 v8, vcc, v80, v5, v80
	v_fma_f32 v9, -v6, v7, 1.0
	v_fmac_f32_e32 v7, v9, v7
	v_mul_f32_e32 v9, v8, v7
	v_fma_f32 v10, -v6, v9, v8
	v_fmac_f32_e32 v9, v10, v7
	v_fma_f32 v6, -v6, v9, v8
	v_div_fmas_f32 v6, v6, v7, v9
	v_div_fixup_f32 v4, v6, v5, v80
	ds_write_b32 v61, v4
	s_waitcnt vmcnt(16)
	v_mul_f32_e32 v5, 0xbfb8aa3b, v81
	v_exp_f32_e32 v5, v5
	s_nop 0
	v_add_f32_e32 v5, 1.0, v5
	v_div_scale_f32 v6, s[24:25], v5, v5, v81
	v_rcp_f32_e32 v7, v6
	v_div_scale_f32 v8, vcc, v81, v5, v81
	v_fma_f32 v9, -v6, v7, 1.0
	v_fmac_f32_e32 v7, v9, v7
	v_mul_f32_e32 v9, v8, v7
	v_fma_f32 v10, -v6, v9, v8
	v_fmac_f32_e32 v9, v10, v7
	v_fma_f32 v6, -v6, v9, v8
	v_div_fmas_f32 v6, v6, v7, v9
	v_div_fixup_f32 v4, v6, v5, v81
	ds_write_b32 v61, v4 offset:2048
	s_waitcnt vmcnt(15)
	v_mul_f32_e32 v5, 0xbfb8aa3b, v82
	v_exp_f32_e32 v5, v5
	s_nop 0
	v_add_f32_e32 v5, 1.0, v5
	v_div_scale_f32 v6, s[24:25], v5, v5, v82
	v_rcp_f32_e32 v7, v6
	v_div_scale_f32 v8, vcc, v82, v5, v82
	v_fma_f32 v9, -v6, v7, 1.0
	v_fmac_f32_e32 v7, v9, v7
	v_mul_f32_e32 v9, v8, v7
	v_fma_f32 v10, -v6, v9, v8
	v_fmac_f32_e32 v9, v10, v7
	v_fma_f32 v6, -v6, v9, v8
	v_div_fmas_f32 v6, v6, v7, v9
	v_div_fixup_f32 v4, v6, v5, v82
	ds_write_b32 v61, v4 offset:4096
	s_waitcnt vmcnt(14)
	v_mul_f32_e32 v5, 0xbfb8aa3b, v83
	v_exp_f32_e32 v5, v5
	s_nop 0
	v_add_f32_e32 v5, 1.0, v5
	v_div_scale_f32 v6, s[24:25], v5, v5, v83
	v_rcp_f32_e32 v7, v6
	v_div_scale_f32 v8, vcc, v83, v5, v83
	v_fma_f32 v9, -v6, v7, 1.0
	v_fmac_f32_e32 v7, v9, v7
	v_mul_f32_e32 v9, v8, v7
	v_fma_f32 v10, -v6, v9, v8
	v_fmac_f32_e32 v9, v10, v7
	v_fma_f32 v6, -v6, v9, v8
	v_div_fmas_f32 v6, v6, v7, v9
	v_div_fixup_f32 v4, v6, v5, v83
	ds_write_b32 v61, v4 offset:6144
	s_waitcnt vmcnt(13)
	v_mul_f32_e32 v5, 0xbfb8aa3b, v84
	v_exp_f32_e32 v5, v5
	s_nop 0
	v_add_f32_e32 v5, 1.0, v5
	v_div_scale_f32 v6, s[24:25], v5, v5, v84
	v_rcp_f32_e32 v7, v6
	v_div_scale_f32 v8, vcc, v84, v5, v84
	v_fma_f32 v9, -v6, v7, 1.0
	v_fmac_f32_e32 v7, v9, v7
	v_mul_f32_e32 v9, v8, v7
	v_fma_f32 v10, -v6, v9, v8
	v_fmac_f32_e32 v9, v10, v7
	v_fma_f32 v6, -v6, v9, v8
	v_div_fmas_f32 v6, v6, v7, v9
	v_div_fixup_f32 v4, v6, v5, v84
	ds_write_b32 v61, v4 offset:8192
	s_waitcnt vmcnt(12)
	v_mul_f32_e32 v5, 0xbfb8aa3b, v85
	v_exp_f32_e32 v5, v5
	s_nop 0
	v_add_f32_e32 v5, 1.0, v5
	v_div_scale_f32 v6, s[24:25], v5, v5, v85
	v_rcp_f32_e32 v7, v6
	v_div_scale_f32 v8, vcc, v85, v5, v85
	v_fma_f32 v9, -v6, v7, 1.0
	v_fmac_f32_e32 v7, v9, v7
	v_mul_f32_e32 v9, v8, v7
	v_fma_f32 v10, -v6, v9, v8
	v_fmac_f32_e32 v9, v10, v7
	v_fma_f32 v6, -v6, v9, v8
	v_div_fmas_f32 v6, v6, v7, v9
	v_div_fixup_f32 v4, v6, v5, v85
	ds_write_b32 v61, v4 offset:10240
	s_waitcnt vmcnt(11)
	v_mul_f32_e32 v5, 0xbfb8aa3b, v86
	v_exp_f32_e32 v5, v5
	s_nop 0
	v_add_f32_e32 v5, 1.0, v5
	v_div_scale_f32 v6, s[24:25], v5, v5, v86
	v_rcp_f32_e32 v7, v6
	v_div_scale_f32 v8, vcc, v86, v5, v86
	v_fma_f32 v9, -v6, v7, 1.0
	v_fmac_f32_e32 v7, v9, v7
	v_mul_f32_e32 v9, v8, v7
	v_fma_f32 v10, -v6, v9, v8
	v_fmac_f32_e32 v9, v10, v7
	v_fma_f32 v6, -v6, v9, v8
	v_div_fmas_f32 v6, v6, v7, v9
	v_div_fixup_f32 v4, v6, v5, v86
	ds_write_b32 v61, v4 offset:12288
	s_waitcnt vmcnt(10)
; DI void phase_init(const Ctx& c) {
;     ...
;       for (int i = tid; i < 9 * 1024; i += NTH) {
;         const int b = i >> 10, k = i & 1023;
;         const float v = b < 8 ? P.in[2][b * 1024 + k] : P.in[3][k];
;         sc[i] = v / (1.f + __expf(-v));
;       }
	v_mul_f32_e32 v5, 0xbfb8aa3b, v87
	v_exp_f32_e32 v5, v5
	s_nop 0
	v_add_f32_e32 v5, 1.0, v5
	v_div_scale_f32 v6, s[24:25], v5, v5, v87
	v_rcp_f32_e32 v7, v6
	v_div_scale_f32 v8, vcc, v87, v5, v87
	v_fma_f32 v9, -v6, v7, 1.0
	v_fmac_f32_e32 v7, v9, v7
	v_mul_f32_e32 v9, v8, v7
	v_fma_f32 v10, -v6, v9, v8
	v_fmac_f32_e32 v9, v10, v7
	v_fma_f32 v6, -v6, v9, v8
	v_div_fmas_f32 v6, v6, v7, v9
	v_div_fixup_f32 v4, v6, v5, v87
	ds_write_b32 v61, v4 offset:14336
	s_waitcnt vmcnt(9)
	v_mul_f32_e32 v5, 0xbfb8aa3b, v88
	v_exp_f32_e32 v5, v5
	s_nop 0
	v_add_f32_e32 v5, 1.0, v5
	v_div_scale_f32 v6, s[24:25], v5, v5, v88
	v_rcp_f32_e32 v7, v6
	v_div_scale_f32 v8, vcc, v88, v5, v88
	v_fma_f32 v9, -v6, v7, 1.0
	v_fmac_f32_e32 v7, v9, v7
	v_mul_f32_e32 v9, v8, v7
	v_fma_f32 v10, -v6, v9, v8
	v_fmac_f32_e32 v9, v10, v7
	v_fma_f32 v6, -v6, v9, v8
	v_div_fmas_f32 v6, v6, v7, v9
	v_div_fixup_f32 v4, v6, v5, v88
	ds_write_b32 v61, v4 offset:16384
	s_waitcnt vmcnt(8)
	v_mul_f32_e32 v5, 0xbfb8aa3b, v89
	v_exp_f32_e32 v5, v5
	s_nop 0
	v_add_f32_e32 v5, 1.0, v5
	v_div_scale_f32 v6, s[24:25], v5, v5, v89
	v_rcp_f32_e32 v7, v6
	v_div_scale_f32 v8, vcc, v89, v5, v89
	v_fma_f32 v9, -v6, v7, 1.0
	v_fmac_f32_e32 v7, v9, v7
	v_mul_f32_e32 v9, v8, v7
	v_fma_f32 v10, -v6, v9, v8
	v_fmac_f32_e32 v9, v10, v7
	v_fma_f32 v6, -v6, v9, v8
	v_div_fmas_f32 v6, v6, v7, v9
	v_div_fixup_f32 v4, v6, v5, v89
	ds_write_b32 v61, v4 offset:18432
	s_waitcnt vmcnt(7)
	v_mul_f32_e32 v5, 0xbfb8aa3b, v90
	v_exp_f32_e32 v5, v5
	s_nop 0
	v_add_f32_e32 v5, 1.0, v5
	v_div_scale_f32 v6, s[24:25], v5, v5, v90
	v_rcp_f32_e32 v7, v6
	v_div_scale_f32 v8, vcc, v90, v5, v90
	v_fma_f32 v9, -v6, v7, 1.0
	v_fmac_f32_e32 v7, v9, v7
	v_mul_f32_e32 v9, v8, v7
	v_fma_f32 v10, -v6, v9, v8
	v_fmac_f32_e32 v9, v10, v7
	v_fma_f32 v6, -v6, v9, v8
	v_div_fmas_f32 v6, v6, v7, v9
	v_div_fixup_f32 v4, v6, v5, v90
	ds_write_b32 v61, v4 offset:20480
	s_waitcnt vmcnt(6)
	v_mul_f32_e32 v5, 0xbfb8aa3b, v91
	v_exp_f32_e32 v5, v5
	s_nop 0
	v_add_f32_e32 v5, 1.0, v5
	v_div_scale_f32 v6, s[24:25], v5, v5, v91
	v_rcp_f32_e32 v7, v6
	v_div_scale_f32 v8, vcc, v91, v5, v91
	v_fma_f32 v9, -v6, v7, 1.0
	v_fmac_f32_e32 v7, v9, v7
	v_mul_f32_e32 v9, v8, v7
	v_fma_f32 v10, -v6, v9, v8
	v_fmac_f32_e32 v9, v10, v7
	v_fma_f32 v6, -v6, v9, v8
	v_div_fmas_f32 v6, v6, v7, v9
	v_div_fixup_f32 v4, v6, v5, v91
	ds_write_b32 v61, v4 offset:22528
	s_waitcnt vmcnt(5)
	v_mul_f32_e32 v5, 0xbfb8aa3b, v92
	v_exp_f32_e32 v5, v5
	s_nop 0
	v_add_f32_e32 v5, 1.0, v5
	v_div_scale_f32 v6, s[24:25], v5, v5, v92
	v_rcp_f32_e32 v7, v6
	v_div_scale_f32 v8, vcc, v92, v5, v92
	v_fma_f32 v9, -v6, v7, 1.0
	v_fmac_f32_e32 v7, v9, v7
	v_mul_f32_e32 v9, v8, v7
	v_fma_f32 v10, -v6, v9, v8
	v_fmac_f32_e32 v9, v10, v7
	v_fma_f32 v6, -v6, v9, v8
	v_div_fmas_f32 v6, v6, v7, v9
	v_div_fixup_f32 v4, v6, v5, v92
	ds_write_b32 v61, v4 offset:24576
	s_waitcnt vmcnt(4)
	v_mul_f32_e32 v5, 0xbfb8aa3b, v93
	v_exp_f32_e32 v5, v5
	s_nop 0
	v_add_f32_e32 v5, 1.0, v5
	v_div_scale_f32 v6, s[24:25], v5, v5, v93
	v_rcp_f32_e32 v7, v6
	v_div_scale_f32 v8, vcc, v93, v5, v93
	v_fma_f32 v9, -v6, v7, 1.0
	v_fmac_f32_e32 v7, v9, v7
	v_mul_f32_e32 v9, v8, v7
	v_fma_f32 v10, -v6, v9, v8
	v_fmac_f32_e32 v9, v10, v7
	v_fma_f32 v6, -v6, v9, v8
	v_div_fmas_f32 v6, v6, v7, v9
	v_div_fixup_f32 v4, v6, v5, v93
	ds_write_b32 v61, v4 offset:26624
	s_waitcnt vmcnt(3)
	v_mul_f32_e32 v5, 0xbfb8aa3b, v94
	v_exp_f32_e32 v5, v5
	s_nop 0
	v_add_f32_e32 v5, 1.0, v5
	v_div_scale_f32 v6, s[24:25], v5, v5, v94
	v_rcp_f32_e32 v7, v6
	v_div_scale_f32 v8, vcc, v94, v5, v94
	v_fma_f32 v9, -v6, v7, 1.0
	v_fmac_f32_e32 v7, v9, v7
	v_mul_f32_e32 v9, v8, v7
	v_fma_f32 v10, -v6, v9, v8
	v_fmac_f32_e32 v9, v10, v7
	v_fma_f32 v6, -v6, v9, v8
	v_div_fmas_f32 v6, v6, v7, v9
	v_div_fixup_f32 v4, v6, v5, v94
	ds_write_b32 v61, v4 offset:28672
	s_waitcnt vmcnt(2)
	v_mul_f32_e32 v5, 0xbfb8aa3b, v95
	v_exp_f32_e32 v5, v5
	s_nop 0
	v_add_f32_e32 v5, 1.0, v5
	v_div_scale_f32 v6, s[24:25], v5, v5, v95
	v_rcp_f32_e32 v7, v6
	v_div_scale_f32 v8, vcc, v95, v5, v95
	v_fma_f32 v9, -v6, v7, 1.0
	v_fmac_f32_e32 v7, v9, v7
	v_mul_f32_e32 v9, v8, v7
	v_fma_f32 v10, -v6, v9, v8
	v_fmac_f32_e32 v9, v10, v7
	v_fma_f32 v6, -v6, v9, v8
	v_div_fmas_f32 v6, v6, v7, v9
	v_div_fixup_f32 v4, v6, v5, v95
	ds_write_b32 v61, v4 offset:30720
	s_waitcnt vmcnt(1)
	v_mul_f32_e32 v5, 0xbfb8aa3b, v96
	v_exp_f32_e32 v5, v5
	s_nop 0
	v_add_f32_e32 v5, 1.0, v5
	v_div_scale_f32 v6, s[24:25], v5, v5, v96
	v_rcp_f32_e32 v7, v6
	v_div_scale_f32 v8, vcc, v96, v5, v96
	v_fma_f32 v9, -v6, v7, 1.0
	v_fmac_f32_e32 v7, v9, v7
	v_mul_f32_e32 v9, v8, v7
	v_fma_f32 v10, -v6, v9, v8
	v_fmac_f32_e32 v9, v10, v7
	v_fma_f32 v6, -v6, v9, v8
	v_div_fmas_f32 v6, v6, v7, v9
	v_div_fixup_f32 v4, v6, v5, v96
	ds_write_b32 v61, v4 offset:32768
	s_waitcnt vmcnt(0)
	v_mul_f32_e32 v5, 0xbfb8aa3b, v97
	v_exp_f32_e32 v5, v5
	s_nop 0
	v_add_f32_e32 v5, 1.0, v5
	v_div_scale_f32 v6, s[24:25], v5, v5, v97
	v_rcp_f32_e32 v7, v6
	v_div_scale_f32 v8, vcc, v97, v5, v97
	v_fma_f32 v9, -v6, v7, 1.0
	v_fmac_f32_e32 v7, v9, v7
	v_mul_f32_e32 v9, v8, v7
	v_fma_f32 v10, -v6, v9, v8
	v_fmac_f32_e32 v9, v10, v7
	v_fma_f32 v6, -v6, v9, v8
	v_div_fmas_f32 v6, v6, v7, v9
	v_div_fixup_f32 v4, v6, v5, v97
	ds_write_b32 v61, v4 offset:34816
